# lnffn gamma/beta kept in AGPRs (loaded once per phase) instead of four load-wait round trips per row
# speedup vs baseline: 1.0403x; 1.0072x over previous
.LBB0_1045:
	s_cmp_lt_i32 s90, 11
	s_cselect_b64 s[0:1], -1, 0
	s_cmp_gt_i32 s91, 10
	s_cselect_b64 s[4:5], -1, 0
	s_and_b64 s[0:1], s[0:1], s[4:5]
	s_andn2_b64 vcc, exec, s[0:1]
	s_cbranch_vccnz .LBB0_1109
	s_waitcnt lgkmcnt(0)
	s_load_dword s3, s[96:97], 0x128
	s_waitcnt vmcnt(0)
	v_mov_b32_e32 v2, v77
	s_add_u32 s6, s96, 0x128
	v_ashrrev_i32_e32 v0, 6, v2
	v_lshl_add_u32 v22, s2, 3, v0
	s_movk_i32 s17, 0x4000
	s_addc_u32 s7, s97, 0
	v_cmp_gt_i32_e32 vcc, s17, v22
	s_and_saveexec_b64 s[8:9], vcc
	s_cbranch_execz .LBB0_1055
	v_readlane_b32 s36, v126, 2
	v_readlane_b32 s42, v126, 8
	v_readlane_b32 s43, v126, 9
	s_add_u32 s4, s42, 0x1d3e8000
	s_addc_u32 s5, s43, 0
	s_waitcnt lgkmcnt(0)
	s_lshl_b32 s24, s3, 3
	s_add_u32 s0, s42, 0x190c8000
	v_ashrrev_i32_e32 v23, 31, v22
	s_addc_u32 s1, s43, 0
	v_and_b32_e32 v3, 15, v2
	v_lshlrev_b64 v[0:1], 6, v[22:23]
	v_lshl_add_u64 v[4:5], s[0:1], 0, v[0:1]
	v_lshlrev_b32_e32 v0, 2, v3
	v_mov_b32_e32 v1, 0
	v_lshlrev_b32_e32 v2, 2, v2
	v_lshl_add_u64 v[6:7], v[4:5], 0, v[0:1]
	v_lshlrev_b64 v[4:5], 11, v[22:23]
	v_and_b32_e32 v20, 0xfc, v2
	v_lshl_add_u64 v[4:5], s[4:5], 0, v[4:5]
	v_lshlrev_b32_e32 v8, 1, v20
	v_mov_b32_e32 v9, v1
	v_lshl_add_u64 v[2:3], v[4:5], 0, v[8:9]
	global_load_dwordx2 v[30:31], v[2:3], off
	global_load_dwordx2 v[28:29], v[2:3], off offset:512
	global_load_dwordx2 v[26:27], v[2:3], off offset:1024
	global_load_dwordx2 v[24:25], v[2:3], off offset:1536
	global_load_dword v5, v[6:7], off
	v_mbcnt_lo_u32_b32 v2, -1, 0
	v_mbcnt_hi_u32_b32 v7, -1, v2
	v_and_b32_e32 v11, 64, v7
	v_xor_b32_e32 v16, 1, v7
	v_lshl_add_u64 v[2:3], s[4:5], 0, v[8:9]
	v_lshl_add_u64 v[14:15], s[42:43], 0, v[8:9]
	v_add_u32_e32 v9, 64, v11
	v_xor_b32_e32 v17, 2, v7
	v_or_b32_e32 v10, 0x300, v20
	v_cmp_lt_i32_e32 vcc, v16, v9
	v_xor_b32_e32 v18, 4, v7
	v_lshlrev_b32_e32 v8, 2, v10
	v_lshl_add_u64 v[10:11], s[0:1], 0, v[0:1]
	v_cndmask_b32_e32 v0, v7, v16, vcc
	v_cmp_lt_i32_e32 vcc, v17, v9
	v_xor_b32_e32 v19, 8, v7
	v_xor_b32_e32 v21, 16, v7
	v_cndmask_b32_e32 v16, v7, v17, vcc
	v_cmp_lt_i32_e32 vcc, v18, v9
	v_xor_b32_e32 v23, 32, v7
	s_mov_b64 s[22:23], 0x333e8000
	v_cndmask_b32_e32 v17, v7, v18, vcc
	v_cmp_lt_i32_e32 vcc, v19, v9
	s_mov_b64 s[30:31], 0x193e8000
	v_or_b32_e32 v4, 0x100, v20
	v_cndmask_b32_e32 v18, v7, v19, vcc
	v_cmp_lt_i32_e32 vcc, v21, v9
	v_or_b32_e32 v6, 0x200, v20
	s_add_u32 s20, s42, 0x18e80000
	v_cndmask_b32_e32 v19, v7, v21, vcc
	v_cmp_lt_i32_e32 vcc, v23, v9
	v_lshlrev_b32_e32 v55, 2, v0
	v_lshlrev_b32_e32 v0, 2, v20
	v_cndmask_b32_e32 v7, v7, v23, vcc
	s_mov_b32 s11, 0
	s_mov_b64 s[12:13], 0
	s_movk_i32 s25, 0x3fff
	s_movk_i32 s26, 0x1fff
	s_movk_i32 s27, 0x6000
	s_mov_b64 s[14:15], 0x5000
	s_mov_b32 s16, 0x3fb504f3
	v_mov_b32_e32 v54, 0x358637bd
	s_mov_b32 s28, 0x800000
	s_mov_b64 s[18:19], 0x1000
	v_lshlrev_b32_e32 v4, 2, v4
	v_lshlrev_b32_e32 v6, 2, v6
	v_lshl_add_u64 v[12:13], v[14:15], 0, s[22:23]
	v_lshl_add_u64 v[14:15], v[14:15], 0, s[30:31]
	s_addc_u32 s21, s43, 0
	v_lshlrev_b32_e32 v56, 2, v16
	v_lshlrev_b32_e32 v57, 2, v17
	v_lshlrev_b32_e32 v58, 2, v18
	v_lshlrev_b32_e32 v59, 2, v19
	v_lshlrev_b32_e32 v60, 2, v7
	v_lshl_add_u64 v[16:17], s[54:55], 0, v[0:1]
	v_lshl_add_u64 v[18:19], s[56:57], 0, v[0:1]
	v_lshlrev_b32_e32 v0, 2, v20
	v_readlane_b32 s37, v126, 3
	v_readlane_b32 s38, v126, 4
	v_readlane_b32 s39, v126, 5
	v_readlane_b32 s40, v126, 6
	v_readlane_b32 s41, v126, 7
	s_waitcnt vmcnt(4)
	v_mov_b64_e32 v[62:63], v[30:31]
	s_waitcnt vmcnt(3)
	v_mov_b64_e32 v[64:65], v[28:29]
	s_waitcnt vmcnt(2)
	v_mov_b64_e32 v[66:67], v[26:27]
	s_waitcnt vmcnt(1)
	v_mov_b64_e32 v[68:69], v[24:25]
	s_waitcnt vmcnt(0)
	v_mov_b32_e32 v61, v5
	global_load_dwordx4 a[8:11], v[16:17], off
	global_load_dwordx4 a[12:15], v[18:19], off
	global_load_dwordx4 a[16:19], v[16:17], off offset:1024
	global_load_dwordx4 a[20:23], v[18:19], off offset:1024
	global_load_dwordx4 a[24:27], v[16:17], off offset:2048
	global_load_dwordx4 a[28:31], v[18:19], off offset:2048
	global_load_dwordx4 a[32:35], v[16:17], off offset:3072
	global_load_dwordx4 a[36:39], v[18:19], off offset:3072
	s_branch .LBB0_1050

.LBB0_1049:
	v_add_u32_e32 v5, 0xffffe000, v22
	v_lshrrev_b32_e32 v5, 11, v5
	v_add_u32_e32 v5, 1, v5
	s_and_b64 s[0:1], exec, vcc
	v_cndmask_b32_e64 v21, 0, v5, s[4:5]
	v_mov_b64_e32 v[48:49], s[20:21]
	s_or_b64 s[12:13], s[0:1], s[12:13]
	v_mad_u64_u32 v[50:51], s[0:1], v21, s27, v[48:49]
	v_lshl_add_u64 v[74:75], v[50:51], 0, s[14:15]
	v_mov_b32_e32 v5, v1
	v_lshl_add_u64 v[50:51], v[74:75], 0, v[0:1]
	v_lshl_add_u64 v[70:71], v[74:75], 0, v[4:5]
	v_mov_b32_e32 v7, v1
	v_mov_b32_e32 v9, v1
	global_load_dwordx4 v[50:53], v[50:51], off
	s_nop 0
	global_load_dwordx4 v[70:73], v[70:71], off
	v_lshl_add_u64 v[78:79], v[74:75], 0, v[6:7]
	v_lshl_add_u64 v[74:75], v[74:75], 0, v[8:9]
	global_load_dwordx4 v[78:81], v[78:79], off
	v_lshlrev_b32_e32 v86, 16, v28
	global_load_dwordx4 v[82:85], v[74:75], off
	v_lshlrev_b32_e32 v74, 16, v30
	v_and_b32_e32 v75, 0xffff0000, v30
	v_lshlrev_b32_e32 v30, 16, v31
	v_and_b32_e32 v31, 0xffff0000, v31
	v_and_b32_e32 v87, 0xffff0000, v28
	v_lshlrev_b32_e32 v28, 16, v29
	v_and_b32_e32 v29, 0xffff0000, v29
	v_lshlrev_b32_e32 v88, 16, v26
	v_and_b32_e32 v89, 0xffff0000, v26
	v_lshlrev_b32_e32 v26, 16, v27
	v_and_b32_e32 v27, 0xffff0000, v27
	v_lshlrev_b32_e32 v90, 16, v24
	v_and_b32_e32 v91, 0xffff0000, v24
	v_lshlrev_b32_e32 v24, 16, v25
	v_and_b32_e32 v25, 0xffff0000, v25
	v_add_u32_e32 v21, 5, v21
	s_waitcnt vmcnt(3)
	v_pk_mul_f32 v[46:47], v[46:47], v[52:53]
	v_pk_mul_f32 v[44:45], v[44:45], v[50:51]
	s_waitcnt vmcnt(2)
	v_pk_mul_f32 v[42:43], v[42:43], v[72:73]
	v_pk_mul_f32 v[40:41], v[40:41], v[70:71]
	s_waitcnt vmcnt(1)
	v_pk_mul_f32 v[50:51], v[38:39], v[80:81]
	v_pk_mul_f32 v[52:53], v[36:37], v[78:79]
	s_waitcnt vmcnt(0)
	v_pk_mul_f32 v[70:71], v[32:33], v[84:85]
	v_pk_mul_f32 v[72:73], v[34:35], v[82:83]
	v_pk_fma_f32 v[36:37], v[74:75], s[16:17], v[44:45] op_sel_hi:[1,0,1]
	v_pk_fma_f32 v[38:39], v[30:31], s[16:17], v[46:47] op_sel_hi:[1,0,1]
	v_pk_fma_f32 v[32:33], v[86:87], s[16:17], v[40:41] op_sel_hi:[1,0,1]
	v_pk_fma_f32 v[34:35], v[28:29], s[16:17], v[42:43] op_sel_hi:[1,0,1]
	v_pk_mov_b32 v[40:41], v[36:37], v[38:39] op_sel:[1,0]
	v_mov_b32_e32 v42, v36
	v_mov_b32_e32 v43, v39
	v_pk_mov_b32 v[44:45], v[32:33], v[34:35] op_sel:[1,0]
	v_mov_b32_e32 v46, v32
	v_mov_b32_e32 v47, v35
	v_pk_add_f32 v[40:41], v[40:41], v[42:43]
	v_pk_add_f32 v[42:43], v[44:45], v[46:47]
	v_pk_fma_f32 v[28:29], v[26:27], s[16:17], v[50:51] op_sel_hi:[1,0,1]
	v_pk_fma_f32 v[30:31], v[88:89], s[16:17], v[52:53] op_sel_hi:[1,0,1]
	v_pk_fma_f32 v[24:25], v[24:25], s[16:17], v[70:71] op_sel_hi:[1,0,1]
	v_pk_fma_f32 v[26:27], v[90:91], s[16:17], v[72:73] op_sel_hi:[1,0,1]
	v_add_f32_e32 v23, v40, v41
	v_pk_add_f32 v[40:41], v[42:43], v[42:43] op_sel:[0,1] op_sel_hi:[1,0]
	v_add_f32_e32 v50, v30, v31
	v_add_f32_e32 v52, v28, v29
	v_mov_b32_e32 v71, v26
	v_mov_b32_e32 v51, v24
	v_mov_b32_e32 v53, v25
	v_add_f32_e32 v70, 0, v23
	v_mov_b32_e32 v41, v27
	v_pk_add_f32 v[44:45], v[50:51], v[52:53]
	v_pk_add_f32 v[40:41], v[70:71], v[40:41]
	s_nop 1
	v_accvgpr_read_b32 v50, a8
	v_accvgpr_read_b32 v51, a9
	v_accvgpr_read_b32 v52, a10
	v_accvgpr_read_b32 v53, a11
	s_nop 1
	v_accvgpr_read_b32 v70, a12
	v_accvgpr_read_b32 v71, a13
	v_accvgpr_read_b32 v72, a14
	v_accvgpr_read_b32 v73, a15
	v_pk_add_f32 v[40:41], v[40:41], v[44:45]
	s_nop 0
	v_add_f32_e32 v23, v40, v41
	v_mov_b32_e32 v40, v23
	s_nop 1
	v_add_f32_dpp v40, v40, v40 quad_perm:[1,0,3,2] row_mask:0xf bank_mask:0xf
	s_nop 1
	v_add_f32_dpp v40, v40, v40 quad_perm:[2,3,0,1] row_mask:0xf bank_mask:0xf
	s_nop 1
	v_add_f32_dpp v40, v40, v40 row_half_mirror row_mask:0xf bank_mask:0xf
	s_nop 1
	v_add_f32_dpp v40, v40, v40 row_mirror row_mask:0xf bank_mask:0xf
	s_nop 0
	v_readlane_b32 s44, v40, 0
	v_readlane_b32 s45, v40, 16
	v_readlane_b32 s46, v40, 32
	v_readlane_b32 s47, v40, 48
	s_nop 1
	v_mov_b32_e32 v40, s44
	v_add_f32_e32 v40, s45, v40
	v_add_f32_e32 v40, s46, v40
	v_add_f32_e32 v40, s47, v40
	v_mov_b32_e32 v23, v40
	v_fmamk_f32 v37, v23, 0xba800000, v37
	v_fmac_f32_e32 v36, 0xba800000, v23
	v_fmamk_f32 v39, v23, 0xba800000, v39
	v_fmac_f32_e32 v38, 0xba800000, v23
	v_fmamk_f32 v33, v23, 0xba800000, v33
	v_fmac_f32_e32 v32, 0xba800000, v23
	v_fmamk_f32 v35, v23, 0xba800000, v35
	v_fmac_f32_e32 v34, 0xba800000, v23
	v_pk_mul_f32 v[40:41], v[38:39], v[38:39]
	v_pk_mul_f32 v[42:43], v[36:37], v[36:37]
	v_pk_mul_f32 v[44:45], v[34:35], v[34:35]
	v_pk_mul_f32 v[46:47], v[32:33], v[32:33]
	v_fmac_f32_e32 v30, 0xba800000, v23
	v_fmac_f32_e32 v28, 0xba800000, v23
	v_pk_mov_b32 v[78:79], v[42:43], v[40:41] op_sel:[1,0]
	v_mov_b32_e32 v43, v41
	v_pk_mov_b32 v[40:41], v[46:47], v[44:45] op_sel:[1,0]
	v_mov_b32_e32 v47, v45
	v_fmamk_f32 v31, v23, 0xba800000, v31
	v_fmamk_f32 v29, v23, 0xba800000, v29
	v_mul_f32_e32 v74, v30, v30
	v_mul_f32_e32 v76, v28, v28
	v_pk_add_f32 v[42:43], v[78:79], v[42:43]
	v_pk_add_f32 v[40:41], v[40:41], v[46:47]
	v_fmamk_f32 v25, v23, 0xba800000, v25
	v_fmac_f32_e32 v24, 0xba800000, v23
	v_fmamk_f32 v27, v23, 0xba800000, v27
	v_fmac_f32_e32 v26, 0xba800000, v23
	v_pk_fma_f32 v[44:45], v[30:31], v[30:31], v[74:75] op_sel_hi:[1,1,0]
	v_pk_fma_f32 v[74:75], v[28:29], v[28:29], v[76:77] op_sel_hi:[1,1,0]
	v_pk_add_f32 v[42:43], v[42:43], v[42:43] op_sel_hi:[0,1]
	v_pk_add_f32 v[40:41], v[40:41], v[40:41] op_sel_hi:[0,1]
	v_mul_f32_e32 v44, v26, v26
	v_mul_f32_e32 v74, v27, v27
	v_mul_f32_e32 v42, v24, v24
	v_mul_f32_e32 v40, v25, v25
	v_pk_add_f32 v[44:45], v[44:45], v[74:75]
	v_pk_add_f32 v[40:41], v[42:43], v[40:41]
	v_mad_u64_u32 v[74:75], s[0:1], v21, s27, v[48:49]
	v_pk_add_f32 v[40:41], v[44:45], v[40:41]
	v_lshl_add_u64 v[42:43], v[74:75], 0, s[18:19]
	v_add_f32_e32 v23, v40, v41
	v_mov_b32_e32 v40, v23
	s_nop 1
	v_add_f32_dpp v40, v40, v40 quad_perm:[1,0,3,2] row_mask:0xf bank_mask:0xf
	s_nop 1
	v_add_f32_dpp v40, v40, v40 quad_perm:[2,3,0,1] row_mask:0xf bank_mask:0xf
	s_nop 1
	v_add_f32_dpp v40, v40, v40 row_half_mirror row_mask:0xf bank_mask:0xf
	s_nop 1
	v_add_f32_dpp v40, v40, v40 row_mirror row_mask:0xf bank_mask:0xf
	s_nop 0
	v_readlane_b32 s44, v40, 0
	v_readlane_b32 s45, v40, 16
	v_readlane_b32 s46, v40, 32
	v_readlane_b32 s47, v40, 48
	s_nop 1
	v_mov_b32_e32 v40, s44
	v_add_f32_e32 v40, s45, v40
	v_add_f32_e32 v40, s46, v40
	v_add_f32_e32 v40, s47, v40
	v_lshl_add_u64 v[46:47], v[42:43], 0, v[0:1]
	v_ashrrev_i32_e32 v23, 31, v22
	v_lshlrev_b64 v[22:23], 11, v[22:23]
	v_mov_b32_e32 v21, v40
	v_fmamk_f32 v21, v21, 0x3a800000, v54
	v_mul_f32_e32 v40, 0x4b800000, v21
	v_cmp_gt_f32_e32 vcc, s28, v21
	s_nop 1
	v_cndmask_b32_e32 v21, v21, v40, vcc
	v_rsq_f32_e32 v21, v21
	v_lshl_add_u64 v[40:41], v[2:3], 0, v[22:23]
	v_lshl_add_u64 v[22:23], v[14:15], 0, v[22:23]
	v_mul_f32_e32 v44, 0x45800000, v21
	v_cndmask_b32_e32 v44, v21, v44, vcc
	v_pk_mul_f32 v[36:37], v[36:37], v[44:45] op_sel_hi:[1,0]
	v_pk_mul_f32 v[38:39], v[38:39], v[44:45] op_sel_hi:[1,0]
	v_pk_fma_f32 v[70:71], v[50:51], v[36:37], v[70:71]
	v_pk_fma_f32 v[38:39], v[52:53], v[38:39], v[72:73]
	v_cvt_pk_bf16_f32 v36, v70, v71
	v_pk_mul_f32 v[32:33], v[32:33], v[44:45] op_sel_hi:[1,0]
	v_cvt_pk_bf16_f32 v37, v38, v39
	global_store_dwordx2 v[40:41], v[36:37], off
	global_load_dwordx4 v[46:49], v[46:47], off
	v_lshl_add_u64 v[36:37], v[74:75], 0, v[0:1]
	global_load_dwordx4 v[50:53], v[36:37], off
	v_pk_mul_f32 v[34:35], v[34:35], v[44:45] op_sel_hi:[1,0]
	v_pk_mul_f32 v[30:31], v[30:31], v[44:45] op_sel_hi:[1,0]
	v_pk_mul_f32 v[28:29], v[28:29], v[44:45] op_sel_hi:[1,0]
	v_pk_mul_f32 v[26:27], v[26:27], v[44:45] op_sel_hi:[1,0]
	v_pk_mul_f32 v[24:25], v[24:25], v[44:45] op_sel_hi:[1,0]
	s_waitcnt vmcnt(1)
	v_pk_add_f32 v[46:47], v[46:47], 1.0 op_sel_hi:[1,0]
	v_pk_add_f32 v[48:49], v[48:49], 1.0 op_sel_hi:[1,0]
	s_waitcnt vmcnt(0)
	v_pk_fma_f32 v[46:47], v[46:47], v[70:71], v[50:51]
	v_pk_fma_f32 v[38:39], v[48:49], v[38:39], v[52:53]
	v_cvt_pk_bf16_f32 v46, v46, v47
	s_nop 0
	v_cvt_pk_bf16_f32 v47, v38, v39
	global_store_dwordx2 v[22:23], v[46:47], off
	s_nop 1
	v_accvgpr_read_b32 v46, a16
	v_accvgpr_read_b32 v47, a17
	v_accvgpr_read_b32 v48, a18
	v_accvgpr_read_b32 v49, a19
	s_nop 0
	s_nop 1
	v_accvgpr_read_b32 v50, a20
	v_accvgpr_read_b32 v51, a21
	v_accvgpr_read_b32 v52, a22
	v_accvgpr_read_b32 v53, a23
	v_lshl_add_u64 v[38:39], v[42:43], 0, v[4:5]
	v_mov_b32_e32 v5, v61
	v_pk_fma_f32 v[52:53], v[48:49], v[34:35], v[52:53]
	v_pk_fma_f32 v[50:51], v[46:47], v[32:33], v[50:51]
	s_nop 0
	v_cvt_pk_bf16_f32 v32, v50, v51
	v_cvt_pk_bf16_f32 v33, v52, v53
	global_store_dwordx2 v[40:41], v[32:33], off offset:512
	global_load_dwordx4 v[32:35], v[38:39], off
	s_nop 0
	global_load_dwordx4 v[46:49], v[36:37], off offset:1024
	v_lshl_add_u64 v[38:39], v[42:43], 0, v[6:7]
	s_waitcnt vmcnt(1)
	v_pk_add_f32 v[32:33], v[32:33], 1.0 op_sel_hi:[1,0]
	v_pk_add_f32 v[34:35], v[34:35], 1.0 op_sel_hi:[1,0]
	s_waitcnt vmcnt(0)
	v_pk_fma_f32 v[32:33], v[32:33], v[50:51], v[46:47]
	v_pk_fma_f32 v[34:35], v[34:35], v[52:53], v[48:49]
	v_cvt_pk_bf16_f32 v32, v32, v33
	s_nop 0
	v_cvt_pk_bf16_f32 v33, v34, v35
	global_store_dwordx2 v[22:23], v[32:33], off offset:512
	s_nop 1
	v_accvgpr_read_b32 v32, a24
	v_accvgpr_read_b32 v33, a25
	v_accvgpr_read_b32 v34, a26
	v_accvgpr_read_b32 v35, a27
	s_nop 0
	s_nop 1
	v_accvgpr_read_b32 v46, a28
	v_accvgpr_read_b32 v47, a29
	v_accvgpr_read_b32 v48, a30
	v_accvgpr_read_b32 v49, a31
	v_pk_fma_f32 v[48:49], v[34:35], v[28:29], v[48:49]
	v_pk_fma_f32 v[46:47], v[32:33], v[30:31], v[46:47]
	s_nop 0
	v_cvt_pk_bf16_f32 v28, v46, v47
	v_cvt_pk_bf16_f32 v29, v48, v49
	global_store_dwordx2 v[40:41], v[28:29], off offset:1024
	global_load_dwordx4 v[28:31], v[38:39], off
	s_nop 0
	global_load_dwordx4 v[32:35], v[36:37], off offset:2048
	v_lshl_add_u64 v[38:39], v[42:43], 0, v[8:9]
	s_waitcnt vmcnt(1)
	v_pk_add_f32 v[28:29], v[28:29], 1.0 op_sel_hi:[1,0]
	v_pk_add_f32 v[30:31], v[30:31], 1.0 op_sel_hi:[1,0]
	s_waitcnt vmcnt(0)
	v_pk_fma_f32 v[28:29], v[28:29], v[46:47], v[32:33]
	v_pk_fma_f32 v[30:31], v[30:31], v[48:49], v[34:35]
	v_cvt_pk_bf16_f32 v28, v28, v29
	s_nop 0
	v_cvt_pk_bf16_f32 v29, v30, v31
	global_store_dwordx2 v[22:23], v[28:29], off offset:1024
	s_nop 1
	v_accvgpr_read_b32 v28, a32
	v_accvgpr_read_b32 v29, a33
	v_accvgpr_read_b32 v30, a34
	v_accvgpr_read_b32 v31, a35
	s_nop 0
	s_nop 1
	v_accvgpr_read_b32 v32, a36
	v_accvgpr_read_b32 v33, a37
	v_accvgpr_read_b32 v34, a38
	v_accvgpr_read_b32 v35, a39
	v_pk_fma_f32 v[42:43], v[24:25], v[30:31], v[34:35]
	v_pk_fma_f32 v[44:45], v[26:27], v[28:29], v[32:33]
	v_mov_b64_e32 v[30:31], v[62:63]
	v_cvt_pk_bf16_f32 v24, v44, v45
	v_cvt_pk_bf16_f32 v25, v42, v43
	global_store_dwordx2 v[40:41], v[24:25], off offset:1536
	global_load_dwordx4 v[32:35], v[38:39], off
	s_nop 0
	global_load_dwordx4 v[36:39], v[36:37], off offset:3072
	v_mov_b64_e32 v[28:29], v[64:65]
	v_mov_b64_e32 v[26:27], v[66:67]
	v_mov_b64_e32 v[24:25], v[68:69]
	s_waitcnt vmcnt(1)
	v_pk_add_f32 v[32:33], v[32:33], 1.0 op_sel_hi:[1,0]
	v_pk_add_f32 v[34:35], v[34:35], 1.0 op_sel_hi:[1,0]
	s_waitcnt vmcnt(0)
	v_pk_fma_f32 v[32:33], v[44:45], v[32:33], v[36:37]
	v_pk_fma_f32 v[34:35], v[42:43], v[34:35], v[38:39]
	v_cvt_pk_bf16_f32 v32, v32, v33
	s_nop 0
	v_cvt_pk_bf16_f32 v33, v34, v35
	global_store_dwordx2 v[22:23], v[32:33], off offset:1536
	v_mov_b32_e32 v22, v20
	s_andn2_b64 exec, exec, s[12:13]
	s_cbranch_execz .LBB0_1055

.LBB0_1646:
	s_cmp_lt_i32 s90, 19
	s_cselect_b64 s[0:1], -1, 0
	s_cmp_gt_i32 s91, 18
	s_cselect_b64 s[4:5], -1, 0
	s_and_b64 s[0:1], s[0:1], s[4:5]
	s_andn2_b64 vcc, exec, s[0:1]
	s_cbranch_vccnz .LBB0_1710
	s_load_dword s13, s[96:97], 0x128
	s_add_u32 s4, s96, 0x128
	v_ashrrev_i32_e32 v0, 6, v77
	s_waitcnt vmcnt(0)
	v_lshl_add_u32 v8, s2, 3, v0
	s_movk_i32 s18, 0x4000
	s_addc_u32 s5, s97, 0
	v_cmp_gt_i32_e32 vcc, s18, v8
	s_waitcnt lgkmcnt(0)
	s_and_saveexec_b64 s[2:3], vcc
	s_cbranch_execz .LBB0_1656
	v_readlane_b32 s20, v126, 2
	v_readlane_b32 s21, v126, 3
	v_readlane_b32 s22, v126, 4
	v_readlane_b32 s23, v126, 5
	v_readlane_b32 s24, v126, 6
	v_readlane_b32 s25, v126, 7
	v_readlane_b32 s26, v126, 8
	v_readlane_b32 s27, v126, 9
	s_mov_b64 s[20:21], s[24:25]
	s_lshl_b32 s19, s13, 3
	s_mov_b64 s[22:23], s[26:27]
	s_add_u32 s6, s22, 0x1d3e8000
	s_addc_u32 s7, s23, 0
	s_add_u32 s0, s56, 0x1000
	s_addc_u32 s1, s57, 0
	s_add_u32 s8, s54, 0x1000
	s_addc_u32 s9, s55, 0
	s_add_u32 s10, s22, 0x190c8000
	v_ashrrev_i32_e32 v9, 31, v8
	s_addc_u32 s11, s23, 0
	v_and_b32_e32 v4, 15, v77
	v_lshlrev_b64 v[0:1], 6, v[8:9]
	v_lshlrev_b32_e32 v6, 2, v77
	v_lshl_add_u64 v[2:3], s[10:11], 0, v[0:1]
	v_lshlrev_b32_e32 v0, 2, v4
	v_mov_b32_e32 v1, 0
	v_lshlrev_b64 v[4:5], 11, v[8:9]
	v_and_b32_e32 v28, 0xfc, v6
	v_lshl_add_u64 v[4:5], s[6:7], 0, v[4:5]
	v_lshlrev_b32_e32 v6, 1, v28
	v_mov_b32_e32 v7, v1
	v_lshl_add_u64 v[4:5], v[4:5], 0, v[6:7]
	v_lshl_add_u64 v[2:3], v[2:3], 0, v[0:1]
	global_load_dwordx2 v[42:43], v[4:5], off
	global_load_dwordx2 v[40:41], v[4:5], off offset:512
	global_load_dwordx2 v[38:39], v[4:5], off offset:1024
	global_load_dwordx2 v[36:37], v[4:5], off offset:1536
	global_load_dword v9, v[2:3], off
	v_lshl_add_u64 v[2:3], s[10:11], 0, v[0:1]
	v_mbcnt_lo_u32_b32 v0, -1, 0
	v_mbcnt_hi_u32_b32 v0, -1, v0
	v_and_b32_e32 v10, 64, v0
	v_add_u32_e32 v10, 64, v10
	v_xor_b32_e32 v11, 1, v0
	v_cmp_lt_i32_e32 vcc, v11, v10
	v_or_b32_e32 v30, 0x100, v28
	v_or_b32_e32 v32, 0x200, v28
	v_cndmask_b32_e32 v11, v0, v11, vcc
	v_lshlrev_b32_e32 v61, 2, v11
	v_xor_b32_e32 v11, 2, v0
	v_cmp_lt_i32_e32 vcc, v11, v10
	v_or_b32_e32 v34, 0x300, v28
	v_lshl_add_u64 v[4:5], s[6:7], 0, v[6:7]
	v_cndmask_b32_e32 v11, v0, v11, vcc
	v_lshlrev_b32_e32 v66, 2, v11
	v_xor_b32_e32 v11, 4, v0
	v_cmp_lt_i32_e32 vcc, v11, v10
	v_lshl_add_u64 v[6:7], s[22:23], 0, v[6:7]
	s_mov_b64 s[6:7], 0x333e8000
	v_cndmask_b32_e32 v11, v0, v11, vcc
	v_lshlrev_b32_e32 v67, 2, v11
	v_xor_b32_e32 v11, 8, v0
	v_cmp_lt_i32_e32 vcc, v11, v10
	v_lshlrev_b32_e32 v16, 2, v30
	v_mov_b32_e32 v17, v1
	v_cndmask_b32_e32 v11, v0, v11, vcc
	v_lshlrev_b32_e32 v68, 2, v11
	v_xor_b32_e32 v11, 16, v0
	v_cmp_lt_i32_e32 vcc, v11, v10
	v_lshlrev_b32_e32 v20, 2, v32
	v_mov_b32_e32 v21, v1
	v_cndmask_b32_e32 v11, v0, v11, vcc
	v_lshlrev_b32_e32 v69, 2, v11
	v_xor_b32_e32 v11, 32, v0
	v_cmp_lt_i32_e32 vcc, v11, v10
	v_lshlrev_b32_e32 v24, 2, v34
	v_mov_b32_e32 v25, v1
	v_cndmask_b32_e32 v0, v0, v11, vcc
	v_lshlrev_b32_e32 v70, 2, v0
	v_lshlrev_b32_e32 v0, 2, v28
	v_lshl_add_u64 v[6:7], v[6:7], 0, s[6:7]
	s_mov_b32 s7, 0
	v_lshl_add_u64 v[10:11], s[8:9], 0, v[0:1]
	v_lshl_add_u64 v[12:13], s[0:1], 0, v[0:1]
	v_lshl_add_u64 v[14:15], s[8:9], 0, v[16:17]
	v_lshl_add_u64 v[16:17], s[0:1], 0, v[16:17]
	v_lshl_add_u64 v[18:19], s[8:9], 0, v[20:21]
	v_lshl_add_u64 v[20:21], s[0:1], 0, v[20:21]
	v_lshl_add_u64 v[22:23], s[8:9], 0, v[24:25]
	v_lshl_add_u64 v[24:25], s[0:1], 0, v[24:25]
	v_lshl_add_u64 v[26:27], s[20:21], 0, v[0:1]
	s_mov_b64 s[8:9], 0
	s_movk_i32 s20, 0x3fff
	s_movk_i32 s21, 0x1fff
	s_movk_i32 s22, 0x6000
	s_mov_b64 s[10:11], 0x18e85000
	v_lshlrev_b32_e32 v0, 2, v28
	s_mov_b32 s12, 0x3fb504f3
	v_lshlrev_b32_e32 v28, 2, v30
	v_lshlrev_b32_e32 v30, 2, v32
	v_lshlrev_b32_e32 v32, 2, v34
	v_mov_b32_e32 v71, 0x358637bd
	s_mov_b32 s23, 0x800000
	s_waitcnt vmcnt(4)
	v_mov_b64_e32 v[72:73], v[42:43]
	s_waitcnt vmcnt(3)
	v_mov_b64_e32 v[74:75], v[40:41]
	s_waitcnt vmcnt(2)
	v_mov_b64_e32 v[76:77], v[38:39]
	s_waitcnt vmcnt(1)
	v_mov_b64_e32 v[78:79], v[36:37]
	s_waitcnt vmcnt(0)
	v_mov_b32_e32 v35, v9
	global_load_dwordx4 a[8:11], v[10:11], off
	global_load_dwordx4 a[12:15], v[12:13], off
	global_load_dwordx4 a[16:19], v[14:15], off
	global_load_dwordx4 a[20:23], v[16:17], off
	global_load_dwordx4 a[24:27], v[18:19], off
	global_load_dwordx4 a[28:31], v[20:21], off
	global_load_dwordx4 a[32:35], v[22:23], off
	global_load_dwordx4 a[36:39], v[24:25], off
	s_branch .LBB0_1651

.LBB0_1650:
	v_add_u32_e32 v9, 0xffffe000, v8
	v_lshrrev_b32_e32 v9, 11, v9
	v_readlane_b32 s24, v126, 2
	v_add_u32_e32 v9, 6, v9
	v_readlane_b32 s30, v126, 8
	v_readlane_b32 s31, v126, 9
	v_cndmask_b32_e64 v9, 5, v9, s[0:1]
	v_mov_b32_e32 v29, v1
	v_mov_b64_e32 v[62:63], s[30:31]
	v_mad_u64_u32 v[62:63], s[0:1], v9, s22, v[62:63]
	v_lshl_add_u64 v[88:89], v[62:63], 0, s[10:11]
	v_lshl_add_u64 v[62:63], v[88:89], 0, v[0:1]
	v_lshl_add_u64 v[80:81], v[88:89], 0, v[28:29]
	v_mov_b32_e32 v31, v1
	global_load_dwordx4 v[62:65], v[62:63], off
	s_nop 0
	global_load_dwordx4 v[80:83], v[80:81], off
	v_lshl_add_u64 v[84:85], v[88:89], 0, v[30:31]
	global_load_dwordx4 v[84:87], v[84:85], off
	v_mov_b32_e32 v33, v1
	v_lshl_add_u64 v[88:89], v[88:89], 0, v[32:33]
	global_load_dwordx4 v[88:91], v[88:89], off
	v_lshlrev_b32_e32 v92, 16, v42
	v_and_b32_e32 v93, 0xffff0000, v42
	v_lshlrev_b32_e32 v42, 16, v43
	v_and_b32_e32 v43, 0xffff0000, v43
	v_lshlrev_b32_e32 v94, 16, v40
	v_and_b32_e32 v95, 0xffff0000, v40
	v_lshlrev_b32_e32 v96, 16, v41
	v_and_b32_e32 v97, 0xffff0000, v41
	v_lshlrev_b32_e32 v100, 16, v36
	v_and_b32_e32 v101, 0xffff0000, v36
	v_lshlrev_b32_e32 v102, 16, v37
	v_and_b32_e32 v103, 0xffff0000, v37
	v_lshlrev_b32_e32 v98, 16, v38
	v_and_b32_e32 v99, 0xffff0000, v38
	v_lshlrev_b32_e32 v38, 16, v39
	v_and_b32_e32 v39, 0xffff0000, v39
	s_and_b64 s[14:15], exec, vcc
	s_or_b64 s[8:9], s[14:15], s[8:9]
	v_readlane_b32 s25, v126, 3
	v_readlane_b32 s26, v126, 4
	v_readlane_b32 s27, v126, 5
	v_readlane_b32 s28, v126, 6
	v_readlane_b32 s29, v126, 7
	s_waitcnt vmcnt(3)
	v_pk_mul_f32 v[36:37], v[58:59], v[64:65]
	v_pk_mul_f32 v[40:41], v[56:57], v[62:63]
	s_waitcnt vmcnt(2)
	v_pk_mul_f32 v[54:55], v[54:55], v[82:83]
	v_pk_mul_f32 v[52:53], v[52:53], v[80:81]
	s_waitcnt vmcnt(1)
	v_pk_mul_f32 v[56:57], v[50:51], v[86:87]
	v_pk_mul_f32 v[58:59], v[48:49], v[84:85]
	v_pk_fma_f32 v[48:49], v[92:93], s[12:13], v[40:41] op_sel_hi:[1,0,1]
	v_pk_fma_f32 v[50:51], v[42:43], s[12:13], v[36:37] op_sel_hi:[1,0,1]
	v_pk_fma_f32 v[40:41], v[94:95], s[12:13], v[52:53] op_sel_hi:[1,0,1]
	v_pk_fma_f32 v[42:43], v[96:97], s[12:13], v[54:55] op_sel_hi:[1,0,1]
	v_pk_fma_f32 v[38:39], v[38:39], s[12:13], v[56:57] op_sel_hi:[1,0,1]
	v_pk_fma_f32 v[36:37], v[98:99], s[12:13], v[58:59] op_sel_hi:[1,0,1]
	v_pk_mov_b32 v[52:53], v[48:49], v[50:51] op_sel:[1,0]
	v_mov_b32_e32 v54, v48
	v_mov_b32_e32 v55, v51
	v_pk_mov_b32 v[56:57], v[40:41], v[42:43] op_sel:[1,0]
	v_mov_b32_e32 v58, v40
	v_mov_b32_e32 v59, v43
	s_waitcnt vmcnt(0)
	v_pk_mul_f32 v[44:45], v[44:45], v[90:91]
	v_pk_mul_f32 v[46:47], v[46:47], v[88:89]
	v_pk_add_f32 v[52:53], v[52:53], v[54:55]
	v_pk_add_f32 v[54:55], v[56:57], v[58:59]
	v_pk_fma_f32 v[44:45], v[102:103], s[12:13], v[44:45] op_sel_hi:[1,0,1]
	v_pk_fma_f32 v[46:47], v[100:101], s[12:13], v[46:47] op_sel_hi:[1,0,1]
	v_add_f32_e32 v9, v52, v53
	v_pk_add_f32 v[52:53], v[54:55], v[54:55] op_sel:[0,1] op_sel_hi:[1,0]
	v_add_f32_e32 v62, v36, v37
	v_add_f32_e32 v64, v38, v39
	v_mov_b32_e32 v81, v46
	v_mov_b32_e32 v63, v44
	v_mov_b32_e32 v65, v45
	v_add_f32_e32 v80, 0, v9
	v_mov_b32_e32 v53, v47
	v_pk_add_f32 v[56:57], v[62:63], v[64:65]
	v_pk_add_f32 v[52:53], v[80:81], v[52:53]
	s_nop 0
	v_pk_add_f32 v[52:53], v[52:53], v[56:57]
	s_nop 0
	v_add_f32_e32 v9, v52, v53
	v_mov_b32_e32 v29, v9
	s_nop 1
	v_add_f32_dpp v29, v29, v29 quad_perm:[1,0,3,2] row_mask:0xf bank_mask:0xf
	s_nop 1
	v_add_f32_dpp v29, v29, v29 quad_perm:[2,3,0,1] row_mask:0xf bank_mask:0xf
	s_nop 1
	v_add_f32_dpp v29, v29, v29 row_half_mirror row_mask:0xf bank_mask:0xf
	s_nop 1
	v_add_f32_dpp v29, v29, v29 row_mirror row_mask:0xf bank_mask:0xf
	s_nop 0
	v_readlane_b32 s44, v29, 0
	v_readlane_b32 s45, v29, 16
	v_readlane_b32 s46, v29, 32
	v_readlane_b32 s47, v29, 48
	s_nop 1
	v_mov_b32_e32 v29, s44
	v_add_f32_e32 v29, s45, v29
	v_add_f32_e32 v29, s46, v29
	v_add_f32_e32 v29, s47, v29
	s_nop 1
	v_accvgpr_read_b32 v52, a8
	v_accvgpr_read_b32 v53, a9
	v_accvgpr_read_b32 v54, a10
	v_accvgpr_read_b32 v55, a11
	s_nop 1
	v_accvgpr_read_b32 v56, a12
	v_accvgpr_read_b32 v57, a13
	v_accvgpr_read_b32 v58, a14
	v_accvgpr_read_b32 v59, a15
	v_mov_b32_e32 v9, v29
	v_fmamk_f32 v49, v9, 0xba800000, v49
	v_fmac_f32_e32 v48, 0xba800000, v9
	v_fmamk_f32 v51, v9, 0xba800000, v51
	v_fmac_f32_e32 v50, 0xba800000, v9
	v_fmamk_f32 v41, v9, 0xba800000, v41
	v_fmac_f32_e32 v40, 0xba800000, v9
	v_fmamk_f32 v43, v9, 0xba800000, v43
	v_fmac_f32_e32 v42, 0xba800000, v9
	v_pk_mul_f32 v[62:63], v[50:51], v[50:51]
	v_pk_mul_f32 v[64:65], v[48:49], v[48:49]
	v_pk_mul_f32 v[80:81], v[42:43], v[42:43]
	v_pk_mul_f32 v[82:83], v[40:41], v[40:41]
	v_fmac_f32_e32 v36, 0xba800000, v9
	v_fmac_f32_e32 v38, 0xba800000, v9
	v_pk_mov_b32 v[86:87], v[64:65], v[62:63] op_sel:[1,0]
	v_mov_b32_e32 v65, v63
	v_pk_mov_b32 v[62:63], v[82:83], v[80:81] op_sel:[1,0]
	v_mov_b32_e32 v83, v81
	v_fmamk_f32 v37, v9, 0xba800000, v37
	v_fmamk_f32 v39, v9, 0xba800000, v39
	v_mul_f32_e32 v60, v36, v36
	v_mul_f32_e32 v84, v38, v38
	v_pk_add_f32 v[64:65], v[86:87], v[64:65]
	v_pk_add_f32 v[62:63], v[62:63], v[82:83]
	v_fmamk_f32 v45, v9, 0xba800000, v45
	v_fmac_f32_e32 v44, 0xba800000, v9
	v_fmamk_f32 v47, v9, 0xba800000, v47
	v_fmac_f32_e32 v46, 0xba800000, v9
	v_pk_fma_f32 v[80:81], v[36:37], v[36:37], v[60:61] op_sel_hi:[1,1,0]
	v_pk_fma_f32 v[84:85], v[38:39], v[38:39], v[84:85] op_sel_hi:[1,1,0]
	v_pk_add_f32 v[64:65], v[64:65], v[64:65] op_sel_hi:[0,1]
	v_pk_add_f32 v[62:63], v[62:63], v[62:63] op_sel_hi:[0,1]
	v_mul_f32_e32 v80, v46, v46
	v_mul_f32_e32 v84, v47, v47
	v_mul_f32_e32 v64, v44, v44
	v_mul_f32_e32 v62, v45, v45
	v_pk_add_f32 v[80:81], v[80:81], v[84:85]
	v_pk_add_f32 v[62:63], v[64:65], v[62:63]
	s_nop 0
	v_pk_add_f32 v[62:63], v[80:81], v[62:63]
	s_nop 0
	v_add_f32_e32 v9, v62, v63
	v_mov_b32_e32 v29, v9
	s_nop 1
	v_add_f32_dpp v29, v29, v29 quad_perm:[1,0,3,2] row_mask:0xf bank_mask:0xf
	s_nop 1
	v_add_f32_dpp v29, v29, v29 quad_perm:[2,3,0,1] row_mask:0xf bank_mask:0xf
	s_nop 1
	v_add_f32_dpp v29, v29, v29 row_half_mirror row_mask:0xf bank_mask:0xf
	s_nop 1
	v_add_f32_dpp v29, v29, v29 row_mirror row_mask:0xf bank_mask:0xf
	s_nop 0
	v_readlane_b32 s44, v29, 0
	v_readlane_b32 s45, v29, 16
	v_readlane_b32 s46, v29, 32
	v_readlane_b32 s47, v29, 48
	s_nop 1
	v_mov_b32_e32 v29, s44
	v_add_f32_e32 v29, s45, v29
	v_add_f32_e32 v29, s46, v29
	v_add_f32_e32 v29, s47, v29
	v_mov_b32_e32 v9, v29
	v_fmamk_f32 v9, v9, 0x3a800000, v71
	v_mul_f32_e32 v29, 0x4b800000, v9
	v_cmp_gt_f32_e32 vcc, s23, v9
	s_nop 1
	v_cndmask_b32_e32 v9, v9, v29, vcc
	v_rsq_f32_e32 v29, v9
	v_ashrrev_i32_e32 v9, 31, v8
	v_lshlrev_b64 v[8:9], 12, v[8:9]
	v_lshl_add_u64 v[62:63], v[26:27], 0, v[8:9]
	v_mul_f32_e32 v8, 0x45800000, v29
	v_cndmask_b32_e32 v8, v29, v8, vcc
	v_pk_mul_f32 v[48:49], v[48:49], v[8:9] op_sel_hi:[1,0]
	v_pk_mul_f32 v[50:51], v[50:51], v[8:9] op_sel_hi:[1,0]
	v_pk_fma_f32 v[48:49], v[52:53], v[48:49], v[56:57]
	v_pk_fma_f32 v[50:51], v[54:55], v[50:51], v[58:59]
	global_store_dwordx4 v[62:63], v[48:51], off
	s_nop 1
	v_accvgpr_read_b32 v48, a16
	v_accvgpr_read_b32 v49, a17
	v_accvgpr_read_b32 v50, a18
	v_accvgpr_read_b32 v51, a19
	s_nop 0
	s_nop 1
	v_accvgpr_read_b32 v52, a20
	v_accvgpr_read_b32 v53, a21
	v_accvgpr_read_b32 v54, a22
	v_accvgpr_read_b32 v55, a23
	v_pk_mul_f32 v[42:43], v[42:43], v[8:9] op_sel_hi:[1,0]
	v_pk_mul_f32 v[40:41], v[40:41], v[8:9] op_sel_hi:[1,0]
	v_pk_mul_f32 v[38:39], v[38:39], v[8:9] op_sel_hi:[1,0]
	v_pk_mul_f32 v[36:37], v[36:37], v[8:9] op_sel_hi:[1,0]
	v_mov_b32_e32 v9, v35
	v_pk_mul_f32 v[56:57], v[44:45], v[8:9] op_sel_hi:[1,0]
	v_pk_mul_f32 v[44:45], v[46:47], v[8:9] op_sel_hi:[1,0]
	v_mov_b32_e32 v8, v34
	v_pk_fma_f32 v[40:41], v[48:49], v[40:41], v[52:53]
	v_pk_fma_f32 v[42:43], v[50:51], v[42:43], v[54:55]
	global_store_dwordx4 v[62:63], v[40:43], off offset:1024
	s_nop 1
	v_accvgpr_read_b32 v40, a24
	v_accvgpr_read_b32 v41, a25
	v_accvgpr_read_b32 v42, a26
	v_accvgpr_read_b32 v43, a27
	s_nop 0
	s_nop 1
	v_accvgpr_read_b32 v48, a28
	v_accvgpr_read_b32 v49, a29
	v_accvgpr_read_b32 v50, a30
	v_accvgpr_read_b32 v51, a31
	v_pk_fma_f32 v[36:37], v[40:41], v[36:37], v[48:49]
	v_pk_fma_f32 v[38:39], v[42:43], v[38:39], v[50:51]
	global_store_dwordx4 v[62:63], v[36:39], off offset:2048
	s_nop 1
	v_accvgpr_read_b32 v48, a32
	v_accvgpr_read_b32 v49, a33
	v_accvgpr_read_b32 v50, a34
	v_accvgpr_read_b32 v51, a35
	s_nop 1
	v_accvgpr_read_b32 v52, a36
	v_accvgpr_read_b32 v53, a37
	v_accvgpr_read_b32 v54, a38
	v_accvgpr_read_b32 v55, a39
	v_mov_b64_e32 v[42:43], v[72:73]
	v_mov_b64_e32 v[40:41], v[74:75]
	v_mov_b64_e32 v[38:39], v[76:77]
	v_mov_b64_e32 v[36:37], v[78:79]
	v_pk_fma_f32 v[44:45], v[48:49], v[44:45], v[52:53]
	v_pk_fma_f32 v[46:47], v[50:51], v[56:57], v[54:55]
	global_store_dwordx4 v[62:63], v[44:47], off offset:3072
	s_andn2_b64 exec, exec, s[8:9]
	s_cbranch_execz .LBB0_1656
